# speedup vs baseline: 1.0065x; 1.0041x over previous
; __device__ void phase_norm_mod(const Params& p, const float* __restrict__ xin, const float* __restrict__ g, const float* __restrict__ sh,
;                                const float* __restrict__ sc) {
;     ...
;     for (int r0 = (gw >> 1) * 2; r0 < SEQ; r0 += GW) {
;         const size_t row = (size_t)b * SEQ + r0;
;         const float4* xr = reinterpret_cast<const float4*>(xin + row * D);
;         float4 v0[4], v1[4];
; #pragma unroll
;         for (int i = 0; i < 4; ++i) { v0[i] = xr[lane + 64 * i]; v1[i] = xr[256 + lane + 64 * i]; }
;         float ss0 = 0.f, ss1 = 0.f;
; #pragma unroll
;         for (int i = 0; i < 4; ++i) { ss0 += sumsq4(v0[i]); ss1 += sumsq4(v1[i]); }
;         ss0 = wave_sum(ss0); ss1 = wave_sum(ss1);
;         const float rs0 = rsqrtf(ss0 * (1.f / D) + EPS), rs1 = rsqrtf(ss1 * (1.f / D) + EPS);
; #pragma unroll
;         for (int i = 0; i < 4; ++i) {
;             const int c = (lane + 64 * i) * 4;
;             u32x2 o0 = {pk2(v0[i].x * rs0 * gm[i].x + sv[i].x, v0[i].y * rs0 * gm[i].y + sv[i].y), pk2(v0[i].z * rs0 * gm[i].z + sv[i].z, v0[i].w * rs0 * gm[i].w + sv[i].w)};
;             u32x2 o1 = {pk2(v1[i].x * rs1 * gm[i].x + sv[i].x, v1[i].y * rs1 * gm[i].y + sv[i].y), pk2(v1[i].z * rs1 * gm[i].z + sv[i].z, v1[i].w * rs1 * gm[i].w + sv[i].w)};
;             *reinterpret_cast<u32x2*>(h + row * D + c) = o0;
;             *reinterpret_cast<u32x2*>(h + (row + 1) * D + c) = o1;
;         }
;     }
.LBB0_527:
	global_load_dwordx4 v[50:53], v[40:41], off offset:-4096
	global_load_dwordx4 v[54:57], v[40:41], off offset:-3072
	global_load_dwordx4 v[62:65], v[40:41], off offset:-2048
	global_load_dwordx4 v[70:73], v[40:41], off offset:-1024
	global_load_dwordx4 v[18:21], v[40:41], off
	global_load_dwordx4 v[58:61], v[40:41], off offset:1024
	global_load_dwordx4 v[66:69], v[40:41], off offset:2048
	global_load_dwordx4 v[74:77], v[40:41], off offset:3072
	v_add_u32_e32 v22, s6, v22
	v_lshl_add_u64 v[40:41], v[40:41], 0, s[8:9]
	s_waitcnt vmcnt(7)
	v_pk_mul_f32 v[80:81], v[50:51], v[50:51]
	v_pk_mul_f32 v[84:85], v[52:53], v[52:53]
	s_waitcnt vmcnt(6)
	v_pk_fma_f32 v[80:81], v[54:55], v[54:55], v[80:81]
	v_pk_fma_f32 v[84:85], v[56:57], v[56:57], v[84:85]
	s_waitcnt vmcnt(5)
	v_pk_fma_f32 v[80:81], v[62:63], v[62:63], v[80:81]
	v_pk_fma_f32 v[84:85], v[64:65], v[64:65], v[84:85]
	s_waitcnt vmcnt(4)
	v_pk_fma_f32 v[80:81], v[70:71], v[70:71], v[80:81]
	v_pk_fma_f32 v[84:85], v[72:73], v[72:73], v[84:85]
	s_waitcnt vmcnt(3)
	v_pk_mul_f32 v[82:83], v[18:19], v[18:19]
	v_pk_mul_f32 v[86:87], v[20:21], v[20:21]
	s_waitcnt vmcnt(2)
	v_pk_fma_f32 v[82:83], v[58:59], v[58:59], v[82:83]
	v_pk_fma_f32 v[86:87], v[60:61], v[60:61], v[86:87]
	s_waitcnt vmcnt(1)
	v_pk_fma_f32 v[82:83], v[66:67], v[66:67], v[82:83]
	v_pk_fma_f32 v[86:87], v[68:69], v[68:69], v[86:87]
	s_waitcnt vmcnt(0)
	v_pk_fma_f32 v[82:83], v[74:75], v[74:75], v[82:83]
	v_pk_fma_f32 v[86:87], v[76:77], v[76:77], v[86:87]
	v_pk_add_f32 v[80:81], v[80:81], v[84:85]
	v_pk_add_f32 v[82:83], v[82:83], v[86:87]
	s_nop 0
	v_add_f32_e32 v79, v80, v81
	v_add_f32_e32 v78, v82, v83
	ds_bpermute_b32 v81, v44, v79
	ds_bpermute_b32 v80, v44, v78
	s_waitcnt lgkmcnt(0)
	v_pk_add_f32 v[78:79], v[78:79], v[80:81]
	ds_bpermute_b32 v81, v45, v79
	ds_bpermute_b32 v80, v45, v78
	s_waitcnt lgkmcnt(0)
	v_pk_add_f32 v[78:79], v[78:79], v[80:81]
	ds_bpermute_b32 v81, v46, v79
	ds_bpermute_b32 v80, v46, v78
	s_waitcnt lgkmcnt(0)
	v_pk_add_f32 v[78:79], v[78:79], v[80:81]
	ds_bpermute_b32 v81, v47, v79
	ds_bpermute_b32 v80, v47, v78
	s_waitcnt lgkmcnt(0)
	v_pk_add_f32 v[78:79], v[78:79], v[80:81]
	ds_bpermute_b32 v81, v48, v79
	ds_bpermute_b32 v80, v48, v78
	s_waitcnt lgkmcnt(0)
	v_pk_add_f32 v[78:79], v[78:79], v[80:81]
	ds_bpermute_b32 v81, v49, v79
	ds_bpermute_b32 v80, v49, v78
	s_waitcnt lgkmcnt(0)
	v_pk_add_f32 v[78:79], v[78:79], v[80:81]
	s_nop 0
	v_pk_fma_f32 v[78:79], v[78:79], s[96:97], v[188:189] op_sel_hi:[1,0,0]
	s_nop 0
	v_mul_f32_e32 v0, 0x4b800000, v79
	v_cmp_gt_f32_e64 s[2:3], s74, v79
	v_cmp_gt_f32_e32 vcc, s74, v78
	s_nop 0
	v_cndmask_b32_e64 v0, v79, v0, s[2:3]
	v_rsq_f32_e32 v0, v0
	s_nop 0
	v_mul_f32_e32 v23, 0x45800000, v0
	v_cndmask_b32_e64 v0, v0, v23, s[2:3]
	v_pk_mul_f32 v[50:51], v[50:51], v[0:1] op_sel_hi:[1,0]
	v_pk_mul_f32 v[52:53], v[52:53], v[0:1] op_sel_hi:[1,0]
	v_pk_fma_f32 v[50:51], v[24:25], v[50:51], v[2:3]
	v_pk_fma_f32 v[52:53], v[26:27], v[52:53], v[4:5]
	v_cvt_pk_bf16_f32 v50, v50, v51
	v_cvt_pk_bf16_f32 v51, v52, v53
	global_store_dwordx2 v[42:43], v[50:51], off offset:-2048
	v_pk_mul_f32 v[50:51], v[54:55], v[0:1] op_sel_hi:[1,0]
	v_pk_mul_f32 v[52:53], v[56:57], v[0:1] op_sel_hi:[1,0]
	v_pk_fma_f32 v[50:51], v[28:29], v[50:51], v[6:7]
	v_pk_fma_f32 v[52:53], v[30:31], v[52:53], v[8:9]
	v_cvt_pk_bf16_f32 v50, v50, v51
	v_cvt_pk_bf16_f32 v51, v52, v53
	global_store_dwordx2 v[42:43], v[50:51], off offset:-1536
	v_pk_mul_f32 v[50:51], v[62:63], v[0:1] op_sel_hi:[1,0]
	v_pk_mul_f32 v[52:53], v[64:65], v[0:1] op_sel_hi:[1,0]
	v_pk_fma_f32 v[50:51], v[32:33], v[50:51], v[10:11]
	v_pk_fma_f32 v[52:53], v[34:35], v[52:53], v[12:13]
	v_cvt_pk_bf16_f32 v50, v50, v51
	v_cvt_pk_bf16_f32 v51, v52, v53
	global_store_dwordx2 v[42:43], v[50:51], off offset:-1024
	v_pk_mul_f32 v[50:51], v[70:71], v[0:1] op_sel_hi:[1,0]
	v_pk_mul_f32 v[52:53], v[72:73], v[0:1] op_sel_hi:[1,0]
	v_mul_f32_e32 v0, 0x4b800000, v78
	v_cndmask_b32_e32 v0, v78, v0, vcc
	v_rsq_f32_e32 v0, v0
	v_pk_fma_f32 v[50:51], v[36:37], v[50:51], v[14:15]
	v_pk_fma_f32 v[52:53], v[38:39], v[52:53], v[16:17]
	s_movk_i32 s2, 0x3fff
	v_mul_f32_e32 v23, 0x45800000, v0
	v_cndmask_b32_e32 v0, v0, v23, vcc
	v_pk_mul_f32 v[18:19], v[18:19], v[0:1] op_sel_hi:[1,0]
	v_pk_mul_f32 v[20:21], v[20:21], v[0:1] op_sel_hi:[1,0]
	v_pk_fma_f32 v[18:19], v[24:25], v[18:19], v[2:3]
	v_pk_fma_f32 v[20:21], v[26:27], v[20:21], v[4:5]
	v_cvt_pk_bf16_f32 v18, v18, v19
	v_cvt_pk_bf16_f32 v19, v20, v21
	global_store_dwordx2 v[42:43], v[18:19], off
	v_pk_mul_f32 v[18:19], v[58:59], v[0:1] op_sel_hi:[1,0]
	v_pk_mul_f32 v[20:21], v[60:61], v[0:1] op_sel_hi:[1,0]
	v_pk_fma_f32 v[18:19], v[28:29], v[18:19], v[6:7]
	v_pk_fma_f32 v[20:21], v[30:31], v[20:21], v[8:9]
	v_cvt_pk_bf16_f32 v18, v18, v19
	v_cvt_pk_bf16_f32 v19, v20, v21
	global_store_dwordx2 v[42:43], v[18:19], off offset:512
	v_pk_mul_f32 v[18:19], v[66:67], v[0:1] op_sel_hi:[1,0]
	v_pk_mul_f32 v[20:21], v[68:69], v[0:1] op_sel_hi:[1,0]
	v_pk_fma_f32 v[18:19], v[32:33], v[18:19], v[10:11]
	v_pk_fma_f32 v[20:21], v[34:35], v[20:21], v[12:13]
	v_cvt_pk_bf16_f32 v18, v18, v19
	v_cvt_pk_bf16_f32 v19, v20, v21
	global_store_dwordx2 v[42:43], v[18:19], off offset:1024
	v_pk_mul_f32 v[18:19], v[74:75], v[0:1] op_sel_hi:[1,0]
	v_pk_mul_f32 v[20:21], v[76:77], v[0:1] op_sel_hi:[1,0]
	v_cvt_pk_bf16_f32 v50, v50, v51
	v_cvt_pk_bf16_f32 v51, v52, v53
	v_pk_fma_f32 v[18:19], v[36:37], v[18:19], v[14:15]
	v_pk_fma_f32 v[20:21], v[38:39], v[20:21], v[16:17]
	v_cmp_lt_i32_e32 vcc, s2, v22
	v_cvt_pk_bf16_f32 v18, v18, v19
	v_cvt_pk_bf16_f32 v19, v20, v21
	global_store_dwordx2 v[42:43], v[50:51], off offset:-512
	global_store_dwordx2 v[42:43], v[18:19], off offset:1536
	v_lshl_add_u64 v[42:43], v[42:43], 0, s[10:11]
	s_or_b64 s[12:13], vcc, s[12:13]
	s_andn2_b64 exec, exec, s[12:13]
	s_cbranch_execnz .LBB0_527

; __device__ void phase_norm_final(const Params& p) {
;     ...
;     for (int row = (blockIdx.x * NWAVES + w) * 2; row < T; row += gridDim.x * NWAVES * 2) {
;         float4* xr = reinterpret_cast<float4*>(p.out + (size_t)row * D);
;         float4 v0[4], v1[4];
; #pragma unroll
;         for (int i = 0; i < 4; ++i) { v0[i] = xr[lane + 64 * i]; v1[i] = xr[256 + lane + 64 * i]; }
;         float ss0 = 0.f, ss1 = 0.f;
; #pragma unroll
;         for (int i = 0; i < 4; ++i) { ss0 += sumsq4(v0[i]); ss1 += sumsq4(v1[i]); }
;         ss0 = wave_sum(ss0); ss1 = wave_sum(ss1);
;         const float rs0 = rsqrtf(ss0 * (1.f / D) + EPS), rs1 = rsqrtf(ss1 * (1.f / D) + EPS);
; #pragma unroll
;         for (int i = 0; i < 4; ++i) {
;             xr[lane + 64 * i] = float4{v0[i].x * rs0 * gg[i].x, v0[i].y * rs0 * gg[i].y, v0[i].z * rs0 * gg[i].z, v0[i].w * rs0 * gg[i].w};
;             xr[256 + lane + 64 * i] = float4{v1[i].x * rs1 * gg[i].x, v1[i].y * rs1 * gg[i].y, v1[i].z * rs1 * gg[i].z, v1[i].w * rs1 * gg[i].w};
;         }
;     }
.LBB0_532:
	v_ashrrev_i32_e32 v51, 31, v50
	v_lshlrev_b64 v[18:19], 12, v[50:51]
	v_lshl_add_u64 v[56:57], v[52:53], 0, v[18:19]
	v_add_co_u32_e32 v54, vcc, 0x1000, v56
	global_load_dwordx4 v[30:33], v[56:57], off
	s_nop 0
	v_addc_co_u32_e32 v55, vcc, 0, v57, vcc
	global_load_dwordx4 v[38:41], v[56:57], off offset:1024
	global_load_dwordx4 v[42:45], v[56:57], off offset:2048
	global_load_dwordx4 v[46:49], v[56:57], off offset:3072
	global_load_dwordx4 v[18:21], v[54:55], off
	global_load_dwordx4 v[22:25], v[54:55], off offset:1024
	global_load_dwordx4 v[26:29], v[54:55], off offset:2048
	global_load_dwordx4 v[34:37], v[54:55], off offset:3072
	v_add_u32_e32 v50, s8, v50
	s_waitcnt vmcnt(7)
	v_pk_mul_f32 v[68:69], v[30:31], v[30:31]
	v_pk_mul_f32 v[70:71], v[32:33], v[32:33]
	s_waitcnt vmcnt(6)
	v_pk_fma_f32 v[68:69], v[38:39], v[38:39], v[68:69]
	v_pk_fma_f32 v[70:71], v[40:41], v[40:41], v[70:71]
	s_waitcnt vmcnt(5)
	v_pk_fma_f32 v[68:69], v[42:43], v[42:43], v[68:69]
	v_pk_fma_f32 v[70:71], v[44:45], v[44:45], v[70:71]
	s_waitcnt vmcnt(4)
	v_pk_fma_f32 v[68:69], v[46:47], v[46:47], v[68:69]
	v_pk_fma_f32 v[70:71], v[48:49], v[48:49], v[70:71]
	s_waitcnt vmcnt(3)
	v_pk_mul_f32 v[72:73], v[18:19], v[18:19]
	v_pk_mul_f32 v[74:75], v[20:21], v[20:21]
	s_waitcnt vmcnt(2)
	v_pk_fma_f32 v[72:73], v[22:23], v[22:23], v[72:73]
	v_pk_fma_f32 v[74:75], v[24:25], v[24:25], v[74:75]
	s_waitcnt vmcnt(1)
	v_pk_fma_f32 v[72:73], v[26:27], v[26:27], v[72:73]
	v_pk_fma_f32 v[74:75], v[28:29], v[28:29], v[74:75]
	s_waitcnt vmcnt(0)
	v_pk_fma_f32 v[72:73], v[34:35], v[34:35], v[72:73]
	v_pk_fma_f32 v[74:75], v[36:37], v[36:37], v[74:75]
	v_pk_add_f32 v[68:69], v[68:69], v[70:71]
	v_pk_add_f32 v[72:73], v[72:73], v[74:75]
	s_nop 0
	v_add_f32_e32 v59, v68, v69
	v_add_f32_e32 v58, v72, v73
	ds_bpermute_b32 v61, v62, v59
	ds_bpermute_b32 v60, v62, v58
	s_waitcnt lgkmcnt(0)
	v_pk_add_f32 v[58:59], v[58:59], v[60:61]
	ds_bpermute_b32 v61, v63, v59
	ds_bpermute_b32 v60, v63, v58
	s_waitcnt lgkmcnt(0)
	v_pk_add_f32 v[58:59], v[58:59], v[60:61]
	ds_bpermute_b32 v61, v64, v59
	ds_bpermute_b32 v60, v64, v58
	s_waitcnt lgkmcnt(0)
	v_pk_add_f32 v[58:59], v[58:59], v[60:61]
	ds_bpermute_b32 v61, v65, v59
	ds_bpermute_b32 v60, v65, v58
	s_waitcnt lgkmcnt(0)
	v_pk_add_f32 v[58:59], v[58:59], v[60:61]
	ds_bpermute_b32 v61, v66, v59
	ds_bpermute_b32 v60, v66, v58
	s_waitcnt lgkmcnt(0)
	v_pk_add_f32 v[58:59], v[58:59], v[60:61]
	ds_bpermute_b32 v61, v67, v59
	ds_bpermute_b32 v60, v67, v58
	s_waitcnt lgkmcnt(0)
	v_pk_add_f32 v[58:59], v[58:59], v[60:61]
	s_nop 0
	v_pk_fma_f32 v[58:59], v[58:59], s[96:97], v[188:189] op_sel_hi:[1,0,0]
	s_nop 0
	v_mul_f32_e32 v0, 0x4b800000, v59
	v_cmp_gt_f32_e64 s[2:3], s74, v59
	v_cmp_gt_f32_e32 vcc, s74, v58
	s_nop 0
	v_cndmask_b32_e64 v0, v59, v0, s[2:3]
	v_rsq_f32_e32 v0, v0
	s_nop 0
	v_mul_f32_e32 v51, 0x45800000, v0
	v_cndmask_b32_e64 v0, v0, v51, s[2:3]
	v_pk_mul_f32 v[30:31], v[30:31], v[0:1] op_sel_hi:[1,0]
	v_pk_mul_f32 v[32:33], v[32:33], v[0:1] op_sel_hi:[1,0]
	v_pk_mul_f32 v[30:31], v[2:3], v[30:31]
	v_pk_mul_f32 v[32:33], v[4:5], v[32:33]
	global_store_dwordx4 v[56:57], v[30:33], off
	s_movk_i32 s2, 0x7fff
	s_nop 0
	v_pk_mul_f32 v[30:31], v[38:39], v[0:1] op_sel_hi:[1,0]
	v_pk_mul_f32 v[32:33], v[40:41], v[0:1] op_sel_hi:[1,0]
	v_pk_mul_f32 v[30:31], v[6:7], v[30:31]
	v_pk_mul_f32 v[32:33], v[8:9], v[32:33]
	global_store_dwordx4 v[56:57], v[30:33], off offset:1024
	s_nop 1
	v_pk_mul_f32 v[30:31], v[42:43], v[0:1] op_sel_hi:[1,0]
	v_pk_mul_f32 v[32:33], v[44:45], v[0:1] op_sel_hi:[1,0]
	v_pk_mul_f32 v[30:31], v[10:11], v[30:31]
	v_pk_mul_f32 v[32:33], v[12:13], v[32:33]
	global_store_dwordx4 v[56:57], v[30:33], off offset:2048
	s_nop 1
	v_pk_mul_f32 v[30:31], v[46:47], v[0:1] op_sel_hi:[1,0]
	v_pk_mul_f32 v[32:33], v[48:49], v[0:1] op_sel_hi:[1,0]
	v_mul_f32_e32 v0, 0x4b800000, v58
	v_cndmask_b32_e32 v0, v58, v0, vcc
	v_rsq_f32_e32 v0, v0
	v_pk_mul_f32 v[30:31], v[14:15], v[30:31]
	v_pk_mul_f32 v[32:33], v[16:17], v[32:33]
	global_store_dwordx4 v[56:57], v[30:33], off offset:3072
	s_nop 1
	v_mul_f32_e32 v30, 0x45800000, v0
	v_cndmask_b32_e32 v0, v0, v30, vcc
	v_pk_mul_f32 v[18:19], v[18:19], v[0:1] op_sel_hi:[1,0]
	v_pk_mul_f32 v[20:21], v[20:21], v[0:1] op_sel_hi:[1,0]
	v_pk_mul_f32 v[18:19], v[2:3], v[18:19]
	v_pk_mul_f32 v[20:21], v[4:5], v[20:21]
	global_store_dwordx4 v[54:55], v[18:21], off
	v_cmp_lt_i32_e32 vcc, s2, v50
	s_or_b64 s[6:7], vcc, s[6:7]
	v_pk_mul_f32 v[18:19], v[22:23], v[0:1] op_sel_hi:[1,0]
	v_pk_mul_f32 v[20:21], v[24:25], v[0:1] op_sel_hi:[1,0]
	v_pk_mul_f32 v[18:19], v[6:7], v[18:19]
	v_pk_mul_f32 v[20:21], v[8:9], v[20:21]
	global_store_dwordx4 v[54:55], v[18:21], off offset:1024
	s_nop 1
	v_pk_mul_f32 v[18:19], v[26:27], v[0:1] op_sel_hi:[1,0]
	v_pk_mul_f32 v[20:21], v[28:29], v[0:1] op_sel_hi:[1,0]
	v_pk_mul_f32 v[18:19], v[10:11], v[18:19]
	v_pk_mul_f32 v[20:21], v[12:13], v[20:21]
	global_store_dwordx4 v[54:55], v[18:21], off offset:2048
	s_nop 1
	v_pk_mul_f32 v[18:19], v[34:35], v[0:1] op_sel_hi:[1,0]
	v_pk_mul_f32 v[20:21], v[36:37], v[0:1] op_sel_hi:[1,0]
	v_pk_mul_f32 v[18:19], v[14:15], v[18:19]
	v_pk_mul_f32 v[20:21], v[16:17], v[20:21]
	global_store_dwordx4 v[54:55], v[18:21], off offset:3072
	s_andn2_b64 exec, exec, s[6:7]
	s_cbranch_execnz .LBB0_532
